# accumulator zeroing with v_mov_b64 (64 instead of 128 moves per GEMM unit), on top of previous
# speedup vs baseline: 1.0032x; 1.0032x over previous
;     __host__ __device__ bool next(int i, Unit& u) const { return tile((long)i * G + c, u); }
;     __host__ __device__ bool next(int i, Unit& u) const { if (!tile((long)(i / NZ) * G + c, u)) return false; u.z = i % NZ; return true; }
; template <class Epi, class Sched, bool ALIGN_EPI = false, bool SP2 = false>
; __device__ __forceinline__ void gemm_phase(PG8_LAS unsigned char* lds, const Gemm g, const Sched& S, const Epi& E, const int wave0) {
;     ...
;         const bool has_next = S.next(ui + 1, nxt);
;         const char* nA = has_next ? (const char*)g.A + (size_t)nxt.z * g.zsA + (size_t)nxt.pm * tstepA + (size_t)nxt.k0 * 2 : cA; const char* nB = has_next ? (const char*)g.Bt + (size_t)nxt.z * g.zsB + (size_t)nxt.pn * tstepB + (size_t)nxt.k0 * 2 : cB;
;         for (int t = 0; t < nt; t += 2) {
;     ...
;         for (int a = 0; a < 2; ++a)
; #pragma unroll
;             for (int b = 0; b < 2; ++b)
; #pragma unroll
;                 for (int m = 0; m < 4; ++m)
; #pragma unroll
;                     for (int n = 0; n < 2; ++n) acc[a][b][m][n] = (f32x4){0.f, 0.f, 0.f, 0.f};
.LBB0_315:
	s_ashr_i32 s11, s10, 31
	s_lshl_b64 s[12:13], s[10:11], 20
	v_readlane_b32 s14, v245, 1
	v_readlane_b32 s15, v245, 2
	s_add_u32 s12, s14, s12
	s_addc_u32 s13, s15, s13
	s_and_b64 s[14:15], s[2:3], exec
	s_cselect_b32 s11, s13, s1
	s_cselect_b32 s33, s12, s0
	s_ashr_i32 s9, s8, 31
	s_lshl_b64 s[14:15], s[8:9], 20
	s_add_u32 s14, s20, s14
	s_addc_u32 s15, s21, s15
	s_and_b64 s[18:19], s[2:3], exec
	s_cselect_b32 s9, s15, s17
	s_cselect_b32 s34, s14, s16
	s_add_u32 s0, s0, 0x80080
	s_addc_u32 s1, s1, 0
	s_add_u32 s35, s16, 0x100
	v_mov_b32_e32 v0, 0
	s_addc_u32 s36, s17, 0
	s_mov_b32 s37, -2
	v_mov_b32_e32 v1, v0
	v_mov_b64_e32 v[2:3], 0
	v_mov_b64_e32 v[4:5], 0
	v_mov_b64_e32 v[6:7], 0
	v_mov_b64_e32 v[8:9], 0
	v_mov_b64_e32 v[10:11], 0
	v_mov_b64_e32 v[12:13], 0
	v_mov_b64_e32 v[14:15], 0
	v_mov_b64_e32 v[24:25], 0
	v_mov_b64_e32 v[26:27], 0
	v_mov_b64_e32 v[28:29], 0
	v_mov_b64_e32 v[30:31], 0
	v_mov_b64_e32 v[40:41], 0
	v_mov_b64_e32 v[42:43], 0
	v_mov_b64_e32 v[44:45], 0
	v_mov_b64_e32 v[46:47], 0
	v_mov_b64_e32 v[16:17], 0
	v_mov_b64_e32 v[18:19], 0
	v_mov_b64_e32 v[20:21], 0
	v_mov_b64_e32 v[22:23], 0
	v_mov_b64_e32 v[32:33], 0
	v_mov_b64_e32 v[34:35], 0
	v_mov_b64_e32 v[36:37], 0
	v_mov_b64_e32 v[38:39], 0
	v_mov_b64_e32 v[48:49], 0
	v_mov_b64_e32 v[50:51], 0
	v_mov_b64_e32 v[52:53], 0
	v_mov_b64_e32 v[54:55], 0
	v_mov_b64_e32 v[56:57], 0
	v_mov_b64_e32 v[58:59], 0
	v_mov_b64_e32 v[60:61], 0
	v_mov_b64_e32 v[62:63], 0
	v_mov_b64_e32 v[66:67], 0
	v_mov_b64_e32 v[68:69], 0
	v_mov_b64_e32 v[70:71], 0
	v_mov_b64_e32 v[72:73], 0
	v_mov_b64_e32 v[74:75], 0
	v_mov_b64_e32 v[76:77], 0
	v_mov_b64_e32 v[78:79], 0
	v_mov_b64_e32 v[80:81], 0
	v_mov_b64_e32 v[90:91], 0
	v_mov_b64_e32 v[92:93], 0
	v_mov_b64_e32 v[94:95], 0
	v_mov_b64_e32 v[96:97], 0
	v_mov_b64_e32 v[106:107], 0
	v_mov_b64_e32 v[108:109], 0
	v_mov_b64_e32 v[110:111], 0
	v_mov_b64_e32 v[112:113], 0
	v_mov_b64_e32 v[82:83], 0
	v_mov_b64_e32 v[84:85], 0
	v_mov_b64_e32 v[86:87], 0
	v_mov_b64_e32 v[88:89], 0
	v_mov_b64_e32 v[98:99], 0
	v_mov_b64_e32 v[100:101], 0
	v_mov_b64_e32 v[102:103], 0
	v_mov_b64_e32 v[104:105], 0
	v_mov_b64_e32 v[114:115], 0
	v_mov_b64_e32 v[116:117], 0
	v_mov_b64_e32 v[118:119], 0
	v_mov_b64_e32 v[120:121], 0
	v_mov_b64_e32 v[122:123], 0
	v_mov_b64_e32 v[124:125], 0
	v_mov_b64_e32 v[126:127], 0
	v_mov_b64_e32 v[128:129], 0
	s_mov_b64 s[42:43], 0x80

;     __host__ __device__ bool next(int i, Unit& u) const { return tile((long)i * G + c, u); }
;     __host__ __device__ bool next(int i, Unit& u) const { if (!tile((long)(i / NZ) * G + c, u)) return false; u.z = i % NZ; return true; }
; template <class Epi, class Sched, bool ALIGN_EPI = false, bool SP2 = false>
; __device__ __forceinline__ void gemm_phase(PG8_LAS unsigned char* lds, const Gemm g, const Sched& S, const Epi& E, const int wave0) {
;     ...
;         const bool has_next = S.next(ui + 1, nxt);
;         const char* nA = has_next ? (const char*)g.A + (size_t)nxt.z * g.zsA + (size_t)nxt.pm * tstepA + (size_t)nxt.k0 * 2 : cA; const char* nB = has_next ? (const char*)g.Bt + (size_t)nxt.z * g.zsB + (size_t)nxt.pn * tstepB + (size_t)nxt.k0 * 2 : cB;
;         for (int t = 0; t < nt; t += 2) {
;     ...
;         for (int a = 0; a < 2; ++a)
; #pragma unroll
;             for (int b = 0; b < 2; ++b)
; #pragma unroll
;                 for (int m = 0; m < 4; ++m)
; #pragma unroll
;                     for (int n = 0; n < 2; ++n) acc[a][b][m][n] = (f32x4){0.f, 0.f, 0.f, 0.f};
.LBB0_1177:
	s_lshl_b64 s[18:19], s[10:11], 22
	s_add_u32 s11, s20, s18
	s_addc_u32 s13, s21, s19
	s_ashr_i32 s9, s8, 31
	s_lshl_b64 s[18:19], s[8:9], 19
	s_add_u32 s46, s11, s18
	s_addc_u32 s47, s13, s19
	s_and_b64 s[2:3], s[2:3], exec
	s_cselect_b32 s9, s47, s17
	s_cselect_b32 s11, s46, s16
	s_add_u32 s0, s0, 0x40080
	s_addc_u32 s1, s1, 0
	s_add_u32 s13, s16, 0x100
	v_mov_b32_e32 v0, 0
	s_addc_u32 s18, s17, 0
	s_mov_b32 s19, -2
	v_mov_b32_e32 v1, v0
	v_mov_b64_e32 v[2:3], 0
	v_mov_b64_e32 v[4:5], 0
	v_mov_b64_e32 v[6:7], 0
	v_mov_b64_e32 v[16:17], 0
	v_mov_b64_e32 v[18:19], 0
	v_mov_b64_e32 v[20:21], 0
	v_mov_b64_e32 v[22:23], 0
	v_mov_b64_e32 v[32:33], 0
	v_mov_b64_e32 v[34:35], 0
	v_mov_b64_e32 v[36:37], 0
	v_mov_b64_e32 v[38:39], 0
	v_mov_b64_e32 v[48:49], 0
	v_mov_b64_e32 v[50:51], 0
	v_mov_b64_e32 v[52:53], 0
	v_mov_b64_e32 v[54:55], 0
	v_mov_b64_e32 v[8:9], 0
	v_mov_b64_e32 v[10:11], 0
	v_mov_b64_e32 v[12:13], 0
	v_mov_b64_e32 v[14:15], 0
	v_mov_b64_e32 v[24:25], 0
	v_mov_b64_e32 v[26:27], 0
	v_mov_b64_e32 v[28:29], 0
	v_mov_b64_e32 v[30:31], 0
	v_mov_b64_e32 v[40:41], 0
	v_mov_b64_e32 v[42:43], 0
	v_mov_b64_e32 v[44:45], 0
	v_mov_b64_e32 v[46:47], 0
	v_mov_b64_e32 v[56:57], 0
	v_mov_b64_e32 v[58:59], 0
	v_mov_b64_e32 v[60:61], 0
	v_mov_b64_e32 v[62:63], 0
	v_mov_b64_e32 v[66:67], 0
	v_mov_b64_e32 v[68:69], 0
	v_mov_b64_e32 v[70:71], 0
	v_mov_b64_e32 v[72:73], 0
	v_mov_b64_e32 v[82:83], 0
	v_mov_b64_e32 v[84:85], 0
	v_mov_b64_e32 v[86:87], 0
	v_mov_b64_e32 v[88:89], 0
	v_mov_b64_e32 v[98:99], 0
	v_mov_b64_e32 v[100:101], 0
	v_mov_b64_e32 v[102:103], 0
	v_mov_b64_e32 v[104:105], 0
	v_mov_b64_e32 v[114:115], 0
	v_mov_b64_e32 v[116:117], 0
	v_mov_b64_e32 v[118:119], 0
	v_mov_b64_e32 v[120:121], 0
	v_mov_b64_e32 v[74:75], 0
	v_mov_b64_e32 v[76:77], 0
	v_mov_b64_e32 v[78:79], 0
	v_mov_b64_e32 v[80:81], 0
	v_mov_b64_e32 v[90:91], 0
	v_mov_b64_e32 v[92:93], 0
	v_mov_b64_e32 v[94:95], 0
	v_mov_b64_e32 v[96:97], 0
	v_mov_b64_e32 v[106:107], 0
	v_mov_b64_e32 v[108:109], 0
	v_mov_b64_e32 v[110:111], 0
	v_mov_b64_e32 v[112:113], 0
	v_mov_b64_e32 v[122:123], 0
	v_mov_b64_e32 v[124:125], 0
	v_mov_b64_e32 v[126:127], 0
	v_mov_b64_e32 v[128:129], 0

;     __host__ __device__ bool next(int i, Unit& u) const { return tile((long)i * G + c, u); }
;     __host__ __device__ bool next(int i, Unit& u) const { if (!tile((long)(i / NZ) * G + c, u)) return false; u.z = i % NZ; return true; }
; template <class Epi, class Sched, bool ALIGN_EPI = false, bool SP2 = false>
; __device__ __forceinline__ void gemm_phase(PG8_LAS unsigned char* lds, const Gemm g, const Sched& S, const Epi& E, const int wave0) {
;     ...
;         const bool has_next = S.next(ui + 1, nxt);
;         const char* nA = has_next ? (const char*)g.A + (size_t)nxt.z * g.zsA + (size_t)nxt.pm * tstepA + (size_t)nxt.k0 * 2 : cA; const char* nB = has_next ? (const char*)g.Bt + (size_t)nxt.z * g.zsB + (size_t)nxt.pn * tstepB + (size_t)nxt.k0 * 2 : cB;
;         for (int t = 0; t < nt; t += 2) {
;     ...
;         for (int a = 0; a < 2; ++a)
; #pragma unroll
;             for (int b = 0; b < 2; ++b)
; #pragma unroll
;                 for (int m = 0; m < 4; ++m)
; #pragma unroll
;                     for (int n = 0; n < 2; ++n) acc[a][b][m][n] = (f32x4){0.f, 0.f, 0.f, 0.f};
.LBB0_1230:
	s_lshl_b64 s[18:19], s[8:9], 22
	s_add_u32 s9, s20, s18
	s_addc_u32 s11, s21, s19
	s_ashr_i32 s13, s12, 31
	s_lshl_b64 s[18:19], s[12:13], 19
	s_add_u32 s44, s9, s18
	s_addc_u32 s45, s11, s19
	s_and_b64 s[2:3], s[2:3], exec
	s_cselect_b32 s9, s45, s17
	s_cselect_b32 s11, s44, s16
	s_add_u32 s0, s0, 0x40080
	s_addc_u32 s1, s1, 0
	s_add_u32 s13, s16, 0x100
	v_mov_b32_e32 v0, 0
	s_addc_u32 s18, s17, 0
	s_mov_b32 s19, -2
	v_mov_b32_e32 v1, v0
	v_mov_b64_e32 v[2:3], 0
	v_mov_b64_e32 v[4:5], 0
	v_mov_b64_e32 v[6:7], 0
	v_mov_b64_e32 v[16:17], 0
	v_mov_b64_e32 v[18:19], 0
	v_mov_b64_e32 v[20:21], 0
	v_mov_b64_e32 v[22:23], 0
	v_mov_b64_e32 v[32:33], 0
	v_mov_b64_e32 v[34:35], 0
	v_mov_b64_e32 v[36:37], 0
	v_mov_b64_e32 v[38:39], 0
	v_mov_b64_e32 v[48:49], 0
	v_mov_b64_e32 v[50:51], 0
	v_mov_b64_e32 v[52:53], 0
	v_mov_b64_e32 v[54:55], 0
	v_mov_b64_e32 v[8:9], 0
	v_mov_b64_e32 v[10:11], 0
	v_mov_b64_e32 v[12:13], 0
	v_mov_b64_e32 v[14:15], 0
	v_mov_b64_e32 v[24:25], 0
	v_mov_b64_e32 v[26:27], 0
	v_mov_b64_e32 v[28:29], 0
	v_mov_b64_e32 v[30:31], 0
	v_mov_b64_e32 v[40:41], 0
	v_mov_b64_e32 v[42:43], 0
	v_mov_b64_e32 v[44:45], 0
	v_mov_b64_e32 v[46:47], 0
	v_mov_b64_e32 v[56:57], 0
	v_mov_b64_e32 v[58:59], 0
	v_mov_b64_e32 v[60:61], 0
	v_mov_b64_e32 v[62:63], 0
	v_mov_b64_e32 v[66:67], 0
	v_mov_b64_e32 v[68:69], 0
	v_mov_b64_e32 v[70:71], 0
	v_mov_b64_e32 v[72:73], 0
	v_mov_b64_e32 v[82:83], 0
	v_mov_b64_e32 v[84:85], 0
	v_mov_b64_e32 v[86:87], 0
	v_mov_b64_e32 v[88:89], 0
	v_mov_b64_e32 v[98:99], 0
	v_mov_b64_e32 v[100:101], 0
	v_mov_b64_e32 v[102:103], 0
	v_mov_b64_e32 v[104:105], 0
	v_mov_b64_e32 v[114:115], 0
	v_mov_b64_e32 v[116:117], 0
	v_mov_b64_e32 v[118:119], 0
	v_mov_b64_e32 v[120:121], 0
	v_mov_b64_e32 v[74:75], 0
	v_mov_b64_e32 v[76:77], 0
	v_mov_b64_e32 v[78:79], 0
	v_mov_b64_e32 v[80:81], 0
	v_mov_b64_e32 v[90:91], 0
	v_mov_b64_e32 v[92:93], 0
	v_mov_b64_e32 v[94:95], 0
	v_mov_b64_e32 v[96:97], 0
	v_mov_b64_e32 v[106:107], 0
	v_mov_b64_e32 v[108:109], 0
	v_mov_b64_e32 v[110:111], 0
	v_mov_b64_e32 v[112:113], 0
	v_mov_b64_e32 v[122:123], 0
	v_mov_b64_e32 v[124:125], 0
	v_mov_b64_e32 v[126:127], 0
	v_mov_b64_e32 v[128:129], 0

;     __host__ __device__ bool next(int i, Unit& u) const { return tile((long)i * G + c, u); }
;     __host__ __device__ bool next(int i, Unit& u) const { if (!tile((long)(i / NZ) * G + c, u)) return false; u.z = i % NZ; return true; }
; template <class Epi, class Sched, bool ALIGN_EPI = false, bool SP2 = false>
; __device__ __forceinline__ void gemm_phase(PG8_LAS unsigned char* lds, const Gemm g, const Sched& S, const Epi& E, const int wave0) {
;     ...
;         const bool has_next = S.next(ui + 1, nxt);
;         const char* nA = has_next ? (const char*)g.A + (size_t)nxt.z * g.zsA + (size_t)nxt.pm * tstepA + (size_t)nxt.k0 * 2 : cA; const char* nB = has_next ? (const char*)g.Bt + (size_t)nxt.z * g.zsB + (size_t)nxt.pn * tstepB + (size_t)nxt.k0 * 2 : cB;
;         for (int t = 0; t < nt; t += 2) {
;     ...
;         for (int a = 0; a < 2; ++a)
; #pragma unroll
;             for (int b = 0; b < 2; ++b)
; #pragma unroll
;                 for (int m = 0; m < 4; ++m)
; #pragma unroll
;                     for (int n = 0; n < 2; ++n) acc[a][b][m][n] = (f32x4){0.f, 0.f, 0.f, 0.f};
.LBB0_1340:
	s_ashr_i32 s11, s10, 31
	s_lshl_b64 s[12:13], s[10:11], 20
	v_readlane_b32 s14, v246, 33
	v_readlane_b32 s15, v246, 34
	s_add_u32 s12, s14, s12
	s_addc_u32 s13, s15, s13
	s_and_b64 s[14:15], s[2:3], exec
	s_cselect_b32 s11, s13, s1
	s_cselect_b32 s33, s12, s0
	s_ashr_i32 s9, s8, 31
	s_lshl_b64 s[14:15], s[8:9], 20
	s_add_u32 s14, s20, s14
	s_addc_u32 s15, s21, s15
	s_and_b64 s[18:19], s[2:3], exec
	s_cselect_b32 s9, s15, s17
	s_cselect_b32 s34, s14, s16
	s_add_u32 s0, s0, 0x80080
	s_addc_u32 s1, s1, 0
	s_add_u32 s35, s16, 0x100
	v_mov_b32_e32 v0, 0
	s_addc_u32 s36, s17, 0
	s_mov_b32 s37, -2
	v_mov_b32_e32 v1, v0
	v_mov_b64_e32 v[2:3], 0
	v_mov_b64_e32 v[4:5], 0
	v_mov_b64_e32 v[6:7], 0
	v_mov_b64_e32 v[8:9], 0
	v_mov_b64_e32 v[10:11], 0
	v_mov_b64_e32 v[12:13], 0
	v_mov_b64_e32 v[14:15], 0
	v_mov_b64_e32 v[24:25], 0
	v_mov_b64_e32 v[26:27], 0
	v_mov_b64_e32 v[28:29], 0
	v_mov_b64_e32 v[30:31], 0
	v_mov_b64_e32 v[40:41], 0
	v_mov_b64_e32 v[42:43], 0
	v_mov_b64_e32 v[44:45], 0
	v_mov_b64_e32 v[46:47], 0
	v_mov_b64_e32 v[16:17], 0
	v_mov_b64_e32 v[18:19], 0
	v_mov_b64_e32 v[20:21], 0
	v_mov_b64_e32 v[22:23], 0
	v_mov_b64_e32 v[32:33], 0
	v_mov_b64_e32 v[34:35], 0
	v_mov_b64_e32 v[36:37], 0
	v_mov_b64_e32 v[38:39], 0
	v_mov_b64_e32 v[48:49], 0
	v_mov_b64_e32 v[50:51], 0
	v_mov_b64_e32 v[52:53], 0
	v_mov_b64_e32 v[54:55], 0
	v_mov_b64_e32 v[56:57], 0
	v_mov_b64_e32 v[58:59], 0
	v_mov_b64_e32 v[60:61], 0
	v_mov_b64_e32 v[62:63], 0
	v_mov_b64_e32 v[66:67], 0
	v_mov_b64_e32 v[68:69], 0
	v_mov_b64_e32 v[70:71], 0
	v_mov_b64_e32 v[72:73], 0
	v_mov_b64_e32 v[74:75], 0
	v_mov_b64_e32 v[76:77], 0
	v_mov_b64_e32 v[78:79], 0
	v_mov_b64_e32 v[80:81], 0
	v_mov_b64_e32 v[90:91], 0
	v_mov_b64_e32 v[92:93], 0
	v_mov_b64_e32 v[94:95], 0
	v_mov_b64_e32 v[96:97], 0
	v_mov_b64_e32 v[106:107], 0
	v_mov_b64_e32 v[108:109], 0
	v_mov_b64_e32 v[110:111], 0
	v_mov_b64_e32 v[112:113], 0
	v_mov_b64_e32 v[82:83], 0
	v_mov_b64_e32 v[84:85], 0
	v_mov_b64_e32 v[86:87], 0
	v_mov_b64_e32 v[88:89], 0
	v_mov_b64_e32 v[98:99], 0
	v_mov_b64_e32 v[100:101], 0
	v_mov_b64_e32 v[102:103], 0
	v_mov_b64_e32 v[104:105], 0
	v_mov_b64_e32 v[114:115], 0
	v_mov_b64_e32 v[116:117], 0
	v_mov_b64_e32 v[118:119], 0
	v_mov_b64_e32 v[120:121], 0
	v_mov_b64_e32 v[122:123], 0
	v_mov_b64_e32 v[124:125], 0
	v_mov_b64_e32 v[126:127], 0
	v_mov_b64_e32 v[128:129], 0
	s_mov_b64 s[44:45], 0x80

;     __host__ __device__ bool next(int i, Unit& u) const { return tile((long)i * G + c, u); }
;     __host__ __device__ bool next(int i, Unit& u) const { if (!tile((long)(i / NZ) * G + c, u)) return false; u.z = i % NZ; return true; }
; template <class Epi, class Sched, bool ALIGN_EPI = false, bool SP2 = false>
; __device__ __forceinline__ void gemm_phase(PG8_LAS unsigned char* lds, const Gemm g, const Sched& S, const Epi& E, const int wave0) {
;     ...
;         const bool has_next = S.next(ui + 1, nxt);
;         const char* nA = has_next ? (const char*)g.A + (size_t)nxt.z * g.zsA + (size_t)nxt.pm * tstepA + (size_t)nxt.k0 * 2 : cA; const char* nB = has_next ? (const char*)g.Bt + (size_t)nxt.z * g.zsB + (size_t)nxt.pn * tstepB + (size_t)nxt.k0 * 2 : cB;
;         for (int t = 0; t < nt; t += 2) {
;     ...
;         for (int a = 0; a < 2; ++a)
; #pragma unroll
;             for (int b = 0; b < 2; ++b)
; #pragma unroll
;                 for (int m = 0; m < 4; ++m)
; #pragma unroll
;                     for (int n = 0; n < 2; ++n) acc[a][b][m][n] = (f32x4){0.f, 0.f, 0.f, 0.f};
.LBB0_1359:
	s_ashr_i32 s27, s26, 31
	s_lshl_b64 s[28:29], s[26:27], 20
	s_add_u32 s11, s20, s28
	s_addc_u32 s13, s21, s29
	s_add_u32 s28, s11, s18
	s_addc_u32 s29, s13, s19
	s_and_b64 s[18:19], s[2:3], exec
	s_cselect_b32 s11, s29, s17
	s_cselect_b32 s13, s28, s16
	s_add_u32 s0, s0, 0x80080
	s_addc_u32 s1, s1, 0
	s_add_u32 s15, s16, 0x100
	v_mov_b32_e32 v0, 0
	s_addc_u32 s27, s17, 0
	s_mov_b32 s41, -2
	v_mov_b32_e32 v1, v0
	v_mov_b64_e32 v[2:3], 0
	v_mov_b64_e32 v[4:5], 0
	v_mov_b64_e32 v[6:7], 0
	v_mov_b64_e32 v[8:9], 0
	v_mov_b64_e32 v[10:11], 0
	v_mov_b64_e32 v[12:13], 0
	v_mov_b64_e32 v[14:15], 0
	v_mov_b64_e32 v[24:25], 0
	v_mov_b64_e32 v[26:27], 0
	v_mov_b64_e32 v[28:29], 0
	v_mov_b64_e32 v[30:31], 0
	v_mov_b64_e32 v[40:41], 0
	v_mov_b64_e32 v[42:43], 0
	v_mov_b64_e32 v[44:45], 0
	v_mov_b64_e32 v[46:47], 0
	v_mov_b64_e32 v[16:17], 0
	v_mov_b64_e32 v[18:19], 0
	v_mov_b64_e32 v[20:21], 0
	v_mov_b64_e32 v[22:23], 0
	v_mov_b64_e32 v[32:33], 0
	v_mov_b64_e32 v[34:35], 0
	v_mov_b64_e32 v[36:37], 0
	v_mov_b64_e32 v[38:39], 0
	v_mov_b64_e32 v[48:49], 0
	v_mov_b64_e32 v[50:51], 0
	v_mov_b64_e32 v[52:53], 0
	v_mov_b64_e32 v[54:55], 0
	v_mov_b64_e32 v[56:57], 0
	v_mov_b64_e32 v[58:59], 0
	v_mov_b64_e32 v[60:61], 0
	v_mov_b64_e32 v[62:63], 0
	v_mov_b64_e32 v[66:67], 0
	v_mov_b64_e32 v[68:69], 0
	v_mov_b64_e32 v[70:71], 0
	v_mov_b64_e32 v[72:73], 0
	v_mov_b64_e32 v[74:75], 0
	v_mov_b64_e32 v[76:77], 0
	v_mov_b64_e32 v[78:79], 0
	v_mov_b64_e32 v[80:81], 0
	v_mov_b64_e32 v[90:91], 0
	v_mov_b64_e32 v[92:93], 0
	v_mov_b64_e32 v[94:95], 0
	v_mov_b64_e32 v[96:97], 0
	v_mov_b64_e32 v[106:107], 0
	v_mov_b64_e32 v[108:109], 0
	v_mov_b64_e32 v[110:111], 0
	v_mov_b64_e32 v[112:113], 0
	v_mov_b64_e32 v[82:83], 0
	v_mov_b64_e32 v[84:85], 0
	v_mov_b64_e32 v[86:87], 0
	v_mov_b64_e32 v[88:89], 0
	v_mov_b64_e32 v[98:99], 0
	v_mov_b64_e32 v[100:101], 0
	v_mov_b64_e32 v[102:103], 0
	v_mov_b64_e32 v[104:105], 0
	v_mov_b64_e32 v[114:115], 0
	v_mov_b64_e32 v[116:117], 0
	v_mov_b64_e32 v[118:119], 0
	v_mov_b64_e32 v[120:121], 0
	v_mov_b64_e32 v[122:123], 0
	v_mov_b64_e32 v[124:125], 0
	v_mov_b64_e32 v[126:127], 0
	v_mov_b64_e32 v[128:129], 0
	s_mov_b64 s[46:47], 0x80

;     __host__ __device__ bool next(int i, Unit& u) const { return tile((long)i * G + c, u); }
;     __host__ __device__ bool next(int i, Unit& u) const { if (!tile((long)(i / NZ) * G + c, u)) return false; u.z = i % NZ; return true; }
; template <class Epi, class Sched, bool ALIGN_EPI = false, bool SP2 = false>
; __device__ __forceinline__ void gemm_phase(PG8_LAS unsigned char* lds, const Gemm g, const Sched& S, const Epi& E, const int wave0) {
;     ...
;         const bool has_next = S.next(ui + 1, nxt);
;         const char* nA = has_next ? (const char*)g.A + (size_t)nxt.z * g.zsA + (size_t)nxt.pm * tstepA + (size_t)nxt.k0 * 2 : cA; const char* nB = has_next ? (const char*)g.Bt + (size_t)nxt.z * g.zsB + (size_t)nxt.pn * tstepB + (size_t)nxt.k0 * 2 : cB;
;         for (int t = 0; t < nt; t += 2) {
;     ...
;         for (int a = 0; a < 2; ++a)
; #pragma unroll
;             for (int b = 0; b < 2; ++b)
; #pragma unroll
;                 for (int m = 0; m < 4; ++m)
; #pragma unroll
;                     for (int n = 0; n < 2; ++n) acc[a][b][m][n] = (f32x4){0.f, 0.f, 0.f, 0.f};
.LBB0_1570:
	s_ashr_i32 s9, s8, 31
	s_lshl_b64 s[10:11], s[8:9], 20
	v_readlane_b32 s12, v245, 1
	v_readlane_b32 s13, v245, 2
	s_add_u32 s10, s12, s10
	s_addc_u32 s11, s13, s11
	s_and_b64 s[12:13], s[42:43], exec
	s_cselect_b32 s9, s11, s1
	s_cselect_b32 s33, s10, s0
	s_ashr_i32 s7, s6, 31
	s_lshl_b64 s[12:13], s[6:7], 20
	s_add_u32 s12, s20, s12
	s_addc_u32 s13, s21, s13
	s_and_b64 s[18:19], s[42:43], exec
	s_cselect_b32 s7, s13, s17
	s_cselect_b32 s36, s12, s16
	s_add_u32 s0, s0, 0x80080
	s_addc_u32 s1, s1, 0
	s_add_u32 s37, s16, 0x100
	v_mov_b32_e32 v0, 0
	s_addc_u32 s44, s17, 0
	s_mov_b32 s45, -2
	v_mov_b32_e32 v1, v0
	v_mov_b64_e32 v[2:3], 0
	v_mov_b64_e32 v[4:5], 0
	v_mov_b64_e32 v[6:7], 0
	v_mov_b64_e32 v[16:17], 0
	v_mov_b64_e32 v[18:19], 0
	v_mov_b64_e32 v[20:21], 0
	v_mov_b64_e32 v[22:23], 0
	v_mov_b64_e32 v[32:33], 0
	v_mov_b64_e32 v[34:35], 0
	v_mov_b64_e32 v[36:37], 0
	v_mov_b64_e32 v[38:39], 0
	v_mov_b64_e32 v[48:49], 0
	v_mov_b64_e32 v[50:51], 0
	v_mov_b64_e32 v[52:53], 0
	v_mov_b64_e32 v[54:55], 0
	v_mov_b64_e32 v[8:9], 0
	v_mov_b64_e32 v[10:11], 0
	v_mov_b64_e32 v[12:13], 0
	v_mov_b64_e32 v[14:15], 0
	v_mov_b64_e32 v[24:25], 0
	v_mov_b64_e32 v[26:27], 0
	v_mov_b64_e32 v[28:29], 0
	v_mov_b64_e32 v[30:31], 0
	v_mov_b64_e32 v[40:41], 0
	v_mov_b64_e32 v[42:43], 0
	v_mov_b64_e32 v[44:45], 0
	v_mov_b64_e32 v[46:47], 0
	v_mov_b64_e32 v[56:57], 0
	v_mov_b64_e32 v[58:59], 0
	v_mov_b64_e32 v[60:61], 0
	v_mov_b64_e32 v[62:63], 0
	v_mov_b64_e32 v[66:67], 0
	v_mov_b64_e32 v[68:69], 0
	v_mov_b64_e32 v[70:71], 0
	v_mov_b64_e32 v[72:73], 0
	v_mov_b64_e32 v[82:83], 0
	v_mov_b64_e32 v[84:85], 0
	v_mov_b64_e32 v[86:87], 0
	v_mov_b64_e32 v[88:89], 0
	v_mov_b64_e32 v[98:99], 0
	v_mov_b64_e32 v[100:101], 0
	v_mov_b64_e32 v[102:103], 0
	v_mov_b64_e32 v[104:105], 0
	v_mov_b64_e32 v[114:115], 0
	v_mov_b64_e32 v[116:117], 0
	v_mov_b64_e32 v[118:119], 0
	v_mov_b64_e32 v[120:121], 0
	v_mov_b64_e32 v[74:75], 0
	v_mov_b64_e32 v[76:77], 0
	v_mov_b64_e32 v[78:79], 0
	v_mov_b64_e32 v[80:81], 0
	v_mov_b64_e32 v[90:91], 0
	v_mov_b64_e32 v[92:93], 0
	v_mov_b64_e32 v[94:95], 0
	v_mov_b64_e32 v[96:97], 0
	v_mov_b64_e32 v[106:107], 0
	v_mov_b64_e32 v[108:109], 0
	v_mov_b64_e32 v[110:111], 0
	v_mov_b64_e32 v[112:113], 0
	v_mov_b64_e32 v[122:123], 0
	v_mov_b64_e32 v[124:125], 0
	v_mov_b64_e32 v[126:127], 0
	v_mov_b64_e32 v[128:129], 0
	s_mov_b64 s[50:51], 0x80

;     __host__ __device__ bool next(int i, Unit& u) const { return tile((long)i * G + c, u); }
;     __host__ __device__ bool next(int i, Unit& u) const { if (!tile((long)(i / NZ) * G + c, u)) return false; u.z = i % NZ; return true; }
; template <class Epi, class Sched, bool ALIGN_EPI = false, bool SP2 = false>
; __device__ __forceinline__ void gemm_phase(PG8_LAS unsigned char* lds, const Gemm g, const Sched& S, const Epi& E, const int wave0) {
;     ...
;         const bool has_next = S.next(ui + 1, nxt);
;         const char* nA = has_next ? (const char*)g.A + (size_t)nxt.z * g.zsA + (size_t)nxt.pm * tstepA + (size_t)nxt.k0 * 2 : cA; const char* nB = has_next ? (const char*)g.Bt + (size_t)nxt.z * g.zsB + (size_t)nxt.pn * tstepB + (size_t)nxt.k0 * 2 : cB;
;         for (int t = 0; t < nt; t += 2) {
;     ...
;         for (int a = 0; a < 2; ++a)
; #pragma unroll
;             for (int b = 0; b < 2; ++b)
; #pragma unroll
;                 for (int m = 0; m < 4; ++m)
; #pragma unroll
;                     for (int n = 0; n < 2; ++n) acc[a][b][m][n] = (f32x4){0.f, 0.f, 0.f, 0.f};
.LBB0_1684:
	s_ashr_i32 s11, s10, 31
	s_lshl_b64 s[12:13], s[10:11], 22
	v_readlane_b32 s14, v246, 44
	v_readlane_b32 s15, v246, 45
	s_add_u32 s12, s14, s12
	s_addc_u32 s13, s15, s13
	s_and_b64 s[14:15], s[2:3], exec
	s_cselect_b32 s11, s13, s1
	s_cselect_b32 s34, s12, s0
	s_ashr_i32 s9, s8, 31
	s_lshl_b64 s[14:15], s[8:9], 22
	s_add_u32 s14, s23, s14
	s_addc_u32 s15, s24, s15
	s_and_b64 s[18:19], s[2:3], exec
	s_cselect_b32 s9, s15, s17
	s_cselect_b32 s35, s14, s16
	s_add_u32 s0, s0, 0x200080
	s_addc_u32 s1, s1, 0
	s_add_u32 s36, s16, 0x100
	v_mov_b32_e32 v0, 0
	s_addc_u32 s37, s17, 0
	s_mov_b32 s42, -2
	v_mov_b32_e32 v1, v0
	v_mov_b64_e32 v[2:3], 0
	v_mov_b64_e32 v[4:5], 0
	v_mov_b64_e32 v[6:7], 0
	v_mov_b64_e32 v[8:9], 0
	v_mov_b64_e32 v[10:11], 0
	v_mov_b64_e32 v[12:13], 0
	v_mov_b64_e32 v[14:15], 0
	v_mov_b64_e32 v[24:25], 0
	v_mov_b64_e32 v[26:27], 0
	v_mov_b64_e32 v[28:29], 0
	v_mov_b64_e32 v[30:31], 0
	v_mov_b64_e32 v[40:41], 0
	v_mov_b64_e32 v[42:43], 0
	v_mov_b64_e32 v[44:45], 0
	v_mov_b64_e32 v[46:47], 0
	v_mov_b64_e32 v[16:17], 0
	v_mov_b64_e32 v[18:19], 0
	v_mov_b64_e32 v[20:21], 0
	v_mov_b64_e32 v[22:23], 0
	v_mov_b64_e32 v[32:33], 0
	v_mov_b64_e32 v[34:35], 0
	v_mov_b64_e32 v[36:37], 0
	v_mov_b64_e32 v[38:39], 0
	v_mov_b64_e32 v[48:49], 0
	v_mov_b64_e32 v[50:51], 0
	v_mov_b64_e32 v[52:53], 0
	v_mov_b64_e32 v[54:55], 0
	v_mov_b64_e32 v[56:57], 0
	v_mov_b64_e32 v[58:59], 0
	v_mov_b64_e32 v[60:61], 0
	v_mov_b64_e32 v[62:63], 0
	v_mov_b64_e32 v[66:67], 0
	v_mov_b64_e32 v[68:69], 0
	v_mov_b64_e32 v[70:71], 0
	v_mov_b64_e32 v[72:73], 0
	v_mov_b64_e32 v[74:75], 0
	v_mov_b64_e32 v[76:77], 0
	v_mov_b64_e32 v[78:79], 0
	v_mov_b64_e32 v[80:81], 0
	v_mov_b64_e32 v[90:91], 0
	v_mov_b64_e32 v[92:93], 0
	v_mov_b64_e32 v[94:95], 0
	v_mov_b64_e32 v[96:97], 0
	v_mov_b64_e32 v[106:107], 0
	v_mov_b64_e32 v[108:109], 0
	v_mov_b64_e32 v[110:111], 0
	v_mov_b64_e32 v[112:113], 0
	v_mov_b64_e32 v[82:83], 0
	v_mov_b64_e32 v[84:85], 0
	v_mov_b64_e32 v[86:87], 0
	v_mov_b64_e32 v[88:89], 0
	v_mov_b64_e32 v[98:99], 0
	v_mov_b64_e32 v[100:101], 0
	v_mov_b64_e32 v[102:103], 0
	v_mov_b64_e32 v[104:105], 0
	v_mov_b64_e32 v[114:115], 0
	v_mov_b64_e32 v[116:117], 0
	v_mov_b64_e32 v[118:119], 0
	v_mov_b64_e32 v[120:121], 0
	v_mov_b64_e32 v[122:123], 0
	v_mov_b64_e32 v[124:125], 0
	v_mov_b64_e32 v[126:127], 0
	v_mov_b64_e32 v[128:129], 0
	s_mov_b64 s[48:49], 0x80

;     __host__ __device__ bool next(int i, Unit& u) const { return tile((long)i * G + c, u); }
;     __host__ __device__ bool next(int i, Unit& u) const { if (!tile((long)(i / NZ) * G + c, u)) return false; u.z = i % NZ; return true; }
; template <class Epi, class Sched, bool ALIGN_EPI = false, bool SP2 = false>
; __device__ __forceinline__ void gemm_phase(PG8_LAS unsigned char* lds, const Gemm g, const Sched& S, const Epi& E, const int wave0) {
;     ...
;         const bool has_next = S.next(ui + 1, nxt);
;         const char* nA = has_next ? (const char*)g.A + (size_t)nxt.z * g.zsA + (size_t)nxt.pm * tstepA + (size_t)nxt.k0 * 2 : cA; const char* nB = has_next ? (const char*)g.Bt + (size_t)nxt.z * g.zsB + (size_t)nxt.pn * tstepB + (size_t)nxt.k0 * 2 : cB;
;         for (int t = 0; t < nt; t += 2) {
;     ...
;         for (int a = 0; a < 2; ++a)
; #pragma unroll
;             for (int b = 0; b < 2; ++b)
; #pragma unroll
;                 for (int m = 0; m < 4; ++m)
; #pragma unroll
;                     for (int n = 0; n < 2; ++n) acc[a][b][m][n] = (f32x4){0.f, 0.f, 0.f, 0.f};
.LBB0_1701:
	s_ashr_i32 s9, s8, 31
	s_lshl_b64 s[14:15], s[8:9], 22
	v_readlane_b32 s20, v246, 44
	v_readlane_b32 s21, v246, 45
	s_add_u32 s9, s20, s14
	s_addc_u32 s13, s21, s15
	s_ashr_i32 s11, s10, 31
	s_lshl_b64 s[20:21], s[10:11], 1
	s_add_u32 s14, s9, s20
	s_addc_u32 s15, s13, s21
	s_and_b64 s[26:27], s[2:3], exec
	s_cselect_b32 s9, s15, s17
	s_cselect_b32 s11, s14, s16
	s_ashr_i32 s13, s12, 31
	s_lshl_b64 s[26:27], s[12:13], 22
	s_add_u32 s13, s23, s26
	s_addc_u32 s27, s24, s27
	s_add_u32 s26, s13, s20
	s_addc_u32 s27, s27, s21
	s_and_b64 s[20:21], s[2:3], exec
	s_cselect_b32 s13, s27, s19
	s_cselect_b32 s38, s26, s18
	s_add_u32 s16, s16, 0x200080
	s_addc_u32 s17, s17, 0
	s_add_u32 s39, s18, 0x100
	v_mov_b32_e32 v0, 0
	s_addc_u32 s42, s19, 0
	s_mov_b32 s43, -2
	v_mov_b32_e32 v1, v0
	v_mov_b64_e32 v[2:3], 0
	v_mov_b64_e32 v[4:5], 0
	v_mov_b64_e32 v[6:7], 0
	v_mov_b64_e32 v[8:9], 0
	v_mov_b64_e32 v[10:11], 0
	v_mov_b64_e32 v[12:13], 0
	v_mov_b64_e32 v[14:15], 0
	v_mov_b64_e32 v[24:25], 0
	v_mov_b64_e32 v[26:27], 0
	v_mov_b64_e32 v[28:29], 0
	v_mov_b64_e32 v[30:31], 0
	v_mov_b64_e32 v[40:41], 0
	v_mov_b64_e32 v[42:43], 0
	v_mov_b64_e32 v[44:45], 0
	v_mov_b64_e32 v[46:47], 0
	v_mov_b64_e32 v[16:17], 0
	v_mov_b64_e32 v[18:19], 0
	v_mov_b64_e32 v[20:21], 0
	v_mov_b64_e32 v[22:23], 0
	v_mov_b64_e32 v[32:33], 0
	v_mov_b64_e32 v[34:35], 0
	v_mov_b64_e32 v[36:37], 0
	v_mov_b64_e32 v[38:39], 0
	v_mov_b64_e32 v[48:49], 0
	v_mov_b64_e32 v[50:51], 0
	v_mov_b64_e32 v[52:53], 0
	v_mov_b64_e32 v[54:55], 0
	v_mov_b64_e32 v[56:57], 0
	v_mov_b64_e32 v[58:59], 0
	v_mov_b64_e32 v[60:61], 0
	v_mov_b64_e32 v[62:63], 0
	v_mov_b64_e32 v[66:67], 0
	v_mov_b64_e32 v[68:69], 0
	v_mov_b64_e32 v[70:71], 0
	v_mov_b64_e32 v[72:73], 0
	v_mov_b64_e32 v[74:75], 0
	v_mov_b64_e32 v[76:77], 0
	v_mov_b64_e32 v[78:79], 0
	v_mov_b64_e32 v[80:81], 0
	v_mov_b64_e32 v[90:91], 0
	v_mov_b64_e32 v[92:93], 0
	v_mov_b64_e32 v[94:95], 0
	v_mov_b64_e32 v[96:97], 0
	v_mov_b64_e32 v[106:107], 0
	v_mov_b64_e32 v[108:109], 0
	v_mov_b64_e32 v[110:111], 0
	v_mov_b64_e32 v[112:113], 0
	v_mov_b64_e32 v[82:83], 0
	v_mov_b64_e32 v[84:85], 0
	v_mov_b64_e32 v[86:87], 0
	v_mov_b64_e32 v[88:89], 0
	v_mov_b64_e32 v[98:99], 0
	v_mov_b64_e32 v[100:101], 0
	v_mov_b64_e32 v[102:103], 0
	v_mov_b64_e32 v[104:105], 0
	v_mov_b64_e32 v[114:115], 0
	v_mov_b64_e32 v[116:117], 0
	v_mov_b64_e32 v[118:119], 0
	v_mov_b64_e32 v[120:121], 0
	v_mov_b64_e32 v[122:123], 0
	v_mov_b64_e32 v[124:125], 0
	v_mov_b64_e32 v[126:127], 0
	v_mov_b64_e32 v[128:129], 0
	s_mov_b64 s[48:49], 0x80
